# grid barrier: first arriver of each XCD round starts the L2 write-back early
# baseline (speedup 1.0000x reference)
; __device__ __forceinline__ unsigned xb_ld(unsigned* p)              { return __hip_atomic_load(p, __ATOMIC_RELAXED, __HIP_MEMORY_SCOPE_AGENT); }
; __device__ __forceinline__ unsigned xb_add(unsigned* p, unsigned v) { return __hip_atomic_fetch_add(p, v, __ATOMIC_RELAXED, __HIP_MEMORY_SCOPE_AGENT); }
; #define XB_SPIN(cond, bar) do { unsigned _sp = 0; while (cond) { __builtin_amdgcn_s_sleep(1); \
;     if ((++_sp & 255u) == 0u) { if (xb_ld(&(bar)[XB_TMO])) break; if (_sp > XB_SPIN_CAP) { atomicAdd(&(bar)[XB_TMO], 1u); break; } } } } while (0)
; __device__ __forceinline__ void xcd_barrier(const XcdBarrier& b) {
;     ...
;         const unsigned old = xb_add(&bar[XB_XSUB(b.x)], 1u);
;         const unsigned gen = old / nloc;
;         if (old + 1u == (gen + 1u) * nloc) {
;             __builtin_amdgcn_fence(__ATOMIC_RELEASE, "agent");
;             asm volatile("s_waitcnt vmcnt(0)" ::: "memory");
;             const unsigned og = xb_add(&bar[XB_TOP], 1u);
;             const unsigned tg = og / nx;
;             if (og + 1u == (tg + 1u) * nx) xb_add(&bar[XB_TOPGEN], 1u);
;             else XB_SPIN(xb_ld(&bar[XB_TOPGEN]) == tg, bar);
;             __builtin_amdgcn_fence(__ATOMIC_ACQUIRE, "agent");
;             xb_add(&bar[XB_XGEN(b.x)], 1u);
;             asm volatile("s_waitcnt vmcnt(0)" ::: "memory");
;         } else {
;             XB_SPIN(xb_ld(&bar[XB_XGEN(b.x)]) == gen, bar);
.LBB0_194:
	s_or_b64 exec, exec, s[8:9]
	v_cvt_f32_u32_e32 v10, v8
	s_waitcnt vmcnt(0)
	v_readfirstlane_b32 s6, v9
	v_sub_u32_e32 v9, 0, v8
	v_rcp_iflag_f32_e32 v10, v10
	v_add_u32_e32 v11, s6, v7
	v_mul_f32_e32 v10, 0x4f7ffffe, v10
	v_cvt_u32_f32_e32 v10, v10
	v_mul_lo_u32 v7, v9, v10
	v_mul_hi_u32 v7, v10, v7
	v_add_u32_e32 v7, v10, v7
	v_mul_hi_u32 v7, v11, v7
	v_mul_lo_u32 v9, v7, v8
	v_sub_u32_e32 v9, v11, v9
	v_add_u32_e32 v10, 1, v7
	v_cmp_ge_u32_e32 vcc, v9, v8
	s_nop 1
	v_cndmask_b32_e32 v7, v7, v10, vcc
	v_sub_u32_e32 v10, v9, v8
	v_cndmask_b32_e32 v9, v9, v10, vcc
	v_add_u32_e32 v10, 1, v7
	v_cmp_ge_u32_e32 vcc, v9, v8
	v_add_u32_e32 v9, 1, v11
	s_nop 0
	v_cndmask_b32_e32 v7, v7, v10, vcc
	v_mul_lo_u32 v10, v8, v7
	v_add_u32_e32 v8, v10, v8
	v_cmp_ne_u32_e32 vcc, v9, v8
	s_and_saveexec_b64 s[6:7], vcc
	s_xor_b64 s[6:7], exec, s[6:7]
	s_cbranch_execz .LBB0_208
	s_waitcnt lgkmcnt(0)
	v_cmp_eq_u32_e32 vcc, v11, v10
	s_cbranch_vccz .Lgb1_nf
	buffer_wbl2 sc1
	s_waitcnt vmcnt(0)
.Lgb1_nf:
	buffer_inv sc1
	v_mov_b32_e32 v6, 0x2000
	global_load_dword v6, v6, s[4:5] offset:1024 sc1
	s_add_u32 s10, s4, 0x2400
	s_addc_u32 s11, s5, 0
	s_waitcnt vmcnt(0)
	v_cmp_eq_u32_e32 vcc, v6, v7
	s_and_saveexec_b64 s[8:9], vcc
	s_cbranch_execz .LBB0_207
	s_mov_b32 s16, 1
	s_mov_b64 s[12:13], 0
	s_branch .LBB0_198
